# X35: gate|up K-loop load segments - LDS-DMA loads take a scalar base plus 32-bit lane offset (no 64-bit vector address adds), ds_reads first, B-fragment LDS addresses hoisted
# speedup vs baseline: 1.0020x; 1.0012x over previous
; #define PG8_STAGE(bufoff, gbase, voff) do { _Pragma("unroll") for (int _i = 0; _i < 2; ++_i) \
;         __builtin_amdgcn_global_load_lds((const unsigned*)((const char*)(gbase) + (voff)[_i]), (PG8_LAS unsigned*)(lds + (bufoff) + ldsw + _i * 8192), 16, 0, 0); } while (0)
; #define PG8_LDA(dst, b, h) do { _Pragma("unroll") for (int m = 0; m < 4; ++m) _Pragma("unroll") for (int k = 0; k < 2; ++k) dst[m][k] = *(const PG8_LAS bf16x8*)(lds + PG8_SA(b, h) + aoff + m * 2048 + k * 1024); } while (0)
; #define PG8_LDB(dst, b, h) do { _Pragma("unroll") for (int n = 0; n < 2; ++n) _Pragma("unroll") for (int k = 0; k < 2; ++k) dst[n][k] = *(const PG8_LAS bf16x8*)(lds + PG8_SB(b, h) + boff + n * 2048 + k * 1024); } while (0)
; #define PG8_MMA(ai, bj, At, Bt) do { __builtin_amdgcn_s_setprio(1); _Pragma("unroll") for (int m = 0; m < 4; ++m) _Pragma("unroll") for (int n = 0; n < 2; ++n) _Pragma("unroll") for (int k = 0; k < 2; ++k) \
;         acc[ai][bj][m][n] = __builtin_amdgcn_mfma_f32_16x16x32_bf16(Bt[n][k], At[m][k], acc[ai][bj][m][n], 0, 0, 0); __builtin_amdgcn_s_setprio(0); } while (0)
; #define PG8_WAIT_V(n) asm volatile("s_waitcnt vmcnt(" #n ")" ::: "memory")
; #define PG8_WAIT_L(n) asm volatile("s_waitcnt lgkmcnt(" #n ")" ::: "memory")
; #define PG8_BAR __builtin_amdgcn_s_barrier()
; #define PG8_SCHED __builtin_amdgcn_sched_barrier(0)
; template <class Epi, class Sched, bool ALIGN_EPI = false, bool SP2 = false>
; __device__ __forceinline__ void gemm_phase(PG8_LAS unsigned char* lds, const Gemm g, const Sched& S, const Epi& E) {
;     ...
;             PG8_LDB(B0, 0, 0); PG8_LDB(B1, 0, 1); PG8_SCHED; PG8_LDA(At, 0, 0); PG8_STAGE(PG8_SA(1, 1), a1 + hstep, voffA);
;             PG8_WAIT_V(8); PG8_WAIT_L(0); PG8_BAR; PG8_MMA(0, 0, At, B0); PG8_MMA(0, 1, At, B1); PG8_BAR; PG8_SCHED;
;             PG8_LDA(At, 0, 1); PG8_STAGE(PG8_SB(0, 0), b2, voffB); PG8_STAGE(PG8_SB(0, 1), b2 + hstep, voffB); PG8_STAGE(PG8_SA(0, 0), a2, voffA);
.LBB0_215:
	s_ashr_i32 s47, s46, 31
	s_lshl_b64 s[50:51], s[46:47], 20
	s_add_u32 s50, s96, s50
	s_addc_u32 s51, s97, s51
	s_and_b64 s[52:53], s[36:37], exec
	s_cselect_b32 s47, s51, s55
	s_cselect_b32 vcc_lo, s50, s54
	s_ashr_i32 s49, s48, 31
	s_lshl_b64 s[52:53], s[48:49], 20
	s_add_u32 s52, s61, s52
	s_addc_u32 s53, s64, s53
	s_and_b64 s[56:57], s[36:37], exec
	s_cselect_b32 s49, s53, s23
	s_cselect_b32 vcc_hi, s52, s22
	s_add_u32 s54, s54, 0x80080
	s_addc_u32 s55, s55, 0
	s_add_u32 s71, s22, 0x100
	s_addc_u32 s77, s23, 0
	s_mov_b32 s20, -2
	v_add_u32_e32 v152, 0x10000, v155
	v_add_u32_e32 v153, 0x14000, v155
	v_add_u32_e32 v192, 0x18000, v155
	v_add_u32_e32 v193, 0x1c000, v155
.LBB0_216:
	ds_read_b128 v[144:147], v152
	ds_read_b128 v[148:151], v152 offset:1024
	ds_read_b128 v[168:171], v152 offset:2048
	ds_read_b128 v[172:175], v152 offset:3072
	ds_read_b128 v[176:179], v153
	ds_read_b128 v[180:183], v153 offset:1024
	ds_read_b128 v[184:187], v153 offset:2048
	ds_read_b128 v[188:191], v153 offset:3072
	ds_read_b128 v[212:215], v157
	ds_read_b128 v[216:219], v157 offset:1024
	ds_read_b128 v[220:223], v157 offset:2048
	ds_read_b128 v[224:227], v157 offset:3072
	ds_read_b128 v[228:231], v157 offset:4096
	ds_read_b128 v[232:235], v157 offset:5120
	ds_read_b128 v[236:239], v157 offset:6144
	ds_read_b128 v[240:243], v157 offset:7168
	s_add_i32 m0, s66, 0xc000
	s_add_u32 s22, s54, 0xfff80080
	s_addc_u32 s23, s55, -1
	global_load_lds_dwordx4 v140, s[54:55]
	s_add_i32 m0, s66, 0xe000
	s_add_i32 s34, 0, 0x10000
	global_load_lds_dwordx4 v142, s[54:55]
	s_cmp_eq_u32 s20, 28
	s_cselect_b32 s57, s47, s23
	s_cselect_b32 s56, vcc_lo, s22
	s_cselect_b32 s23, s49, s77
	s_cselect_b32 s22, vcc_hi, s71
	s_add_i32 s4, 0, 0x14000
	s_waitcnt vmcnt(8)
	s_waitcnt lgkmcnt(0)
	s_barrier
	v_mfma_f32_16x16x32_bf16 v[126:129], v[144:147], v[212:215], v[126:129]
	v_mfma_f32_16x16x32_bf16 v[126:129], v[148:151], v[216:219], v[126:129]
	v_mfma_f32_16x16x32_bf16 v[118:121], v[168:171], v[212:215], v[118:121]
	v_mfma_f32_16x16x32_bf16 v[118:121], v[172:175], v[216:219], v[118:121]
	v_mfma_f32_16x16x32_bf16 v[130:133], v[176:179], v[212:215], v[130:133]
	v_mfma_f32_16x16x32_bf16 v[130:133], v[180:183], v[216:219], v[130:133]
	v_mfma_f32_16x16x32_bf16 v[122:125], v[184:187], v[212:215], v[122:125]
	v_mfma_f32_16x16x32_bf16 v[122:125], v[188:191], v[216:219], v[122:125]
	v_mfma_f32_16x16x32_bf16 v[106:109], v[184:187], v[220:223], v[106:109]
	v_mfma_f32_16x16x32_bf16 v[106:109], v[188:191], v[224:227], v[106:109]
	v_mfma_f32_16x16x32_bf16 v[114:117], v[176:179], v[220:223], v[114:117]
	v_mfma_f32_16x16x32_bf16 v[114:117], v[180:183], v[224:227], v[114:117]
	v_mfma_f32_16x16x32_bf16 v[102:105], v[168:171], v[220:223], v[102:105]
	v_mfma_f32_16x16x32_bf16 v[102:105], v[172:175], v[224:227], v[102:105]
	v_mfma_f32_16x16x32_bf16 v[110:113], v[144:147], v[220:223], v[110:113]
	v_mfma_f32_16x16x32_bf16 v[110:113], v[148:151], v[224:227], v[110:113]
	v_mfma_f32_16x16x32_bf16 v[94:97], v[144:147], v[228:231], v[94:97]
	v_mfma_f32_16x16x32_bf16 v[94:97], v[148:151], v[232:235], v[94:97]
	v_mfma_f32_16x16x32_bf16 v[86:89], v[168:171], v[228:231], v[86:89]
	v_mfma_f32_16x16x32_bf16 v[86:89], v[172:175], v[232:235], v[86:89]
	v_mfma_f32_16x16x32_bf16 v[98:101], v[176:179], v[228:231], v[98:101]
	v_mfma_f32_16x16x32_bf16 v[98:101], v[180:183], v[232:235], v[98:101]
	v_mfma_f32_16x16x32_bf16 v[90:93], v[184:187], v[228:231], v[90:93]
	v_mfma_f32_16x16x32_bf16 v[90:93], v[188:191], v[232:235], v[90:93]
	v_mfma_f32_16x16x32_bf16 v[74:77], v[184:187], v[236:239], v[74:77]
	v_mfma_f32_16x16x32_bf16 v[74:77], v[188:191], v[240:243], v[74:77]
	v_mfma_f32_16x16x32_bf16 v[82:85], v[176:179], v[236:239], v[82:85]
	v_mfma_f32_16x16x32_bf16 v[82:85], v[180:183], v[240:243], v[82:85]
	v_mfma_f32_16x16x32_bf16 v[70:73], v[168:171], v[236:239], v[70:73]
	v_mfma_f32_16x16x32_bf16 v[70:73], v[172:175], v[240:243], v[70:73]
	v_mfma_f32_16x16x32_bf16 v[78:81], v[144:147], v[236:239], v[78:81]
	v_mfma_f32_16x16x32_bf16 v[78:81], v[148:151], v[240:243], v[78:81]
	s_barrier
	ds_read_b128 v[212:215], v157 offset:16384
	ds_read_b128 v[216:219], v157 offset:17408
	ds_read_b128 v[220:223], v157 offset:18432
	ds_read_b128 v[224:227], v157 offset:19456
	ds_read_b128 v[228:231], v157 offset:20480
	ds_read_b128 v[232:235], v157 offset:21504
	ds_read_b128 v[236:239], v157 offset:22528
	ds_read_b128 v[240:243], v157 offset:23552
	s_add_i32 s5, s34, s65
	s_mov_b32 m0, s5
	s_add_u32 s34, s22, 0x80000
	s_addc_u32 s35, s23, 0
	global_load_lds_dwordx4 v4, s[22:23]
	s_add_i32 m0, s5, 0x2000
	s_add_i32 s4, s4, s65
	global_load_lds_dwordx4 v2, s[22:23]
	s_mov_b32 m0, s4
	s_nop 0
	global_load_lds_dwordx4 v4, s[34:35]
	s_add_i32 m0, s4, 0x2000
	s_nop 0
	global_load_lds_dwordx4 v2, s[34:35]
	s_mov_b32 m0, s66
	s_nop 0
	global_load_lds_dwordx4 v136, s[56:57]
	s_mov_b32 m0, s67
	s_nop 0
	global_load_lds_dwordx4 v134, s[56:57]
	s_waitcnt vmcnt(8)
	s_waitcnt lgkmcnt(0)
	s_barrier
; #define PG8_STAGE(bufoff, gbase, voff) do { _Pragma("unroll") for (int _i = 0; _i < 2; ++_i) \
;         __builtin_amdgcn_global_load_lds((const unsigned*)((const char*)(gbase) + (voff)[_i]), (PG8_LAS unsigned*)(lds + (bufoff) + ldsw + _i * 8192), 16, 0, 0); } while (0)
; #define PG8_LDA(dst, b, h) do { _Pragma("unroll") for (int m = 0; m < 4; ++m) _Pragma("unroll") for (int k = 0; k < 2; ++k) dst[m][k] = *(const PG8_LAS bf16x8*)(lds + PG8_SA(b, h) + aoff + m * 2048 + k * 1024); } while (0)
; #define PG8_LDB(dst, b, h) do { _Pragma("unroll") for (int n = 0; n < 2; ++n) _Pragma("unroll") for (int k = 0; k < 2; ++k) dst[n][k] = *(const PG8_LAS bf16x8*)(lds + PG8_SB(b, h) + boff + n * 2048 + k * 1024); } while (0)
; #define PG8_MMA(ai, bj, At, Bt) do { __builtin_amdgcn_s_setprio(1); _Pragma("unroll") for (int m = 0; m < 4; ++m) _Pragma("unroll") for (int n = 0; n < 2; ++n) _Pragma("unroll") for (int k = 0; k < 2; ++k) \
;         acc[ai][bj][m][n] = __builtin_amdgcn_mfma_f32_16x16x32_bf16(Bt[n][k], At[m][k], acc[ai][bj][m][n], 0, 0, 0); __builtin_amdgcn_s_setprio(0); } while (0)
; #define PG8_WAIT_V(n) asm volatile("s_waitcnt vmcnt(" #n ")" ::: "memory")
; #define PG8_WAIT_L(n) asm volatile("s_waitcnt lgkmcnt(" #n ")" ::: "memory")
; #define PG8_BAR __builtin_amdgcn_s_barrier()
; #define PG8_SCHED __builtin_amdgcn_sched_barrier(0)
; template <class Epi, class Sched, bool ALIGN_EPI = false, bool SP2 = false>
; __device__ __forceinline__ void gemm_phase(PG8_LAS unsigned char* lds, const Gemm g, const Sched& S, const Epi& E) {
;     ...
;             PG8_WAIT_V(8); PG8_WAIT_L(0); PG8_BAR; PG8_MMA(1, 0, At, B0); PG8_MMA(1, 1, At, B1); PG8_BAR; PG8_SCHED;
;             PG8_LDB(B0, 1, 0); PG8_LDB(B1, 1, 1); PG8_SCHED; PG8_LDA(At, 1, 0); PG8_STAGE(PG8_SA(0, 1), a2 + hstep, voffA);
;             PG8_WAIT_V(8); PG8_WAIT_L(0); PG8_BAR; PG8_MMA(0, 0, At, B0); PG8_MMA(0, 1, At, B1); PG8_BAR; PG8_SCHED;
	v_mfma_f32_16x16x32_bf16 v[62:65], v[144:147], v[212:215], v[62:65]
	v_mfma_f32_16x16x32_bf16 v[62:65], v[148:151], v[216:219], v[62:65]
	v_mfma_f32_16x16x32_bf16 v[54:57], v[168:171], v[212:215], v[54:57]
	v_mfma_f32_16x16x32_bf16 v[54:57], v[172:175], v[216:219], v[54:57]
	v_mfma_f32_16x16x32_bf16 v[66:69], v[176:179], v[212:215], v[66:69]
	v_mfma_f32_16x16x32_bf16 v[66:69], v[180:183], v[216:219], v[66:69]
	v_mfma_f32_16x16x32_bf16 v[58:61], v[184:187], v[212:215], v[58:61]
	v_mfma_f32_16x16x32_bf16 v[58:61], v[188:191], v[216:219], v[58:61]
	v_mfma_f32_16x16x32_bf16 v[42:45], v[184:187], v[220:223], v[42:45]
	v_mfma_f32_16x16x32_bf16 v[42:45], v[188:191], v[224:227], v[42:45]
	v_mfma_f32_16x16x32_bf16 v[50:53], v[176:179], v[220:223], v[50:53]
	v_mfma_f32_16x16x32_bf16 v[50:53], v[180:183], v[224:227], v[50:53]
	v_mfma_f32_16x16x32_bf16 v[38:41], v[168:171], v[220:223], v[38:41]
	v_mfma_f32_16x16x32_bf16 v[38:41], v[172:175], v[224:227], v[38:41]
	v_mfma_f32_16x16x32_bf16 v[46:49], v[144:147], v[220:223], v[46:49]
	v_mfma_f32_16x16x32_bf16 v[46:49], v[148:151], v[224:227], v[46:49]
	v_mfma_f32_16x16x32_bf16 v[30:33], v[144:147], v[228:231], v[30:33]
	v_mfma_f32_16x16x32_bf16 v[30:33], v[148:151], v[232:235], v[30:33]
	v_mfma_f32_16x16x32_bf16 v[22:25], v[168:171], v[228:231], v[22:25]
	v_mfma_f32_16x16x32_bf16 v[22:25], v[172:175], v[232:235], v[22:25]
	v_mfma_f32_16x16x32_bf16 v[34:37], v[176:179], v[228:231], v[34:37]
	v_mfma_f32_16x16x32_bf16 v[34:37], v[180:183], v[232:235], v[34:37]
	v_mfma_f32_16x16x32_bf16 v[26:29], v[184:187], v[228:231], v[26:29]
	v_mfma_f32_16x16x32_bf16 v[26:29], v[188:191], v[232:235], v[26:29]
	v_mfma_f32_16x16x32_bf16 v[10:13], v[184:187], v[236:239], v[10:13]
	v_mfma_f32_16x16x32_bf16 v[10:13], v[188:191], v[240:243], v[10:13]
	v_mfma_f32_16x16x32_bf16 v[18:21], v[176:179], v[236:239], v[18:21]
	v_mfma_f32_16x16x32_bf16 v[18:21], v[180:183], v[240:243], v[18:21]
	v_mfma_f32_16x16x32_bf16 v[6:9], v[168:171], v[236:239], v[6:9]
	v_mfma_f32_16x16x32_bf16 v[6:9], v[172:175], v[240:243], v[6:9]
	v_mfma_f32_16x16x32_bf16 v[14:17], v[144:147], v[236:239], v[14:17]
	v_mfma_f32_16x16x32_bf16 v[14:17], v[148:151], v[240:243], v[14:17]
	s_barrier
	ds_read_b128 v[144:147], v192
	ds_read_b128 v[148:151], v192 offset:1024
	ds_read_b128 v[168:171], v192 offset:2048
	ds_read_b128 v[172:175], v192 offset:3072
	ds_read_b128 v[176:179], v193
	ds_read_b128 v[180:183], v193 offset:1024
	ds_read_b128 v[184:187], v193 offset:2048
	ds_read_b128 v[188:191], v193 offset:3072
	ds_read_b128 v[212:215], v157 offset:32768
	ds_read_b128 v[216:219], v157 offset:33792
	ds_read_b128 v[220:223], v157 offset:34816
	ds_read_b128 v[224:227], v157 offset:35840
	ds_read_b128 v[228:231], v157 offset:36864
	ds_read_b128 v[232:235], v157 offset:37888
	ds_read_b128 v[236:239], v157 offset:38912
	ds_read_b128 v[240:243], v157 offset:39936
	s_add_u32 s34, s56, 0x80000
	s_addc_u32 s35, s57, 0
	s_mov_b32 m0, s60
	s_add_i32 s4, 0, 0x18000
	global_load_lds_dwordx4 v136, s[34:35]
	s_mov_b32 m0, s2
	s_add_i32 s5, 0, 0x1c000
	global_load_lds_dwordx4 v134, s[34:35]
	s_waitcnt vmcnt(8)
	s_waitcnt lgkmcnt(0)
	s_barrier
	v_mfma_f32_16x16x32_bf16 v[126:129], v[144:147], v[212:215], v[126:129]
	v_mfma_f32_16x16x32_bf16 v[126:129], v[148:151], v[216:219], v[126:129]
	v_mfma_f32_16x16x32_bf16 v[118:121], v[168:171], v[212:215], v[118:121]
	v_mfma_f32_16x16x32_bf16 v[118:121], v[172:175], v[216:219], v[118:121]
	v_mfma_f32_16x16x32_bf16 v[130:133], v[176:179], v[212:215], v[130:133]
	v_mfma_f32_16x16x32_bf16 v[130:133], v[180:183], v[216:219], v[130:133]
	v_mfma_f32_16x16x32_bf16 v[122:125], v[184:187], v[212:215], v[122:125]
	v_mfma_f32_16x16x32_bf16 v[122:125], v[188:191], v[216:219], v[122:125]
	v_mfma_f32_16x16x32_bf16 v[106:109], v[184:187], v[220:223], v[106:109]
	v_mfma_f32_16x16x32_bf16 v[106:109], v[188:191], v[224:227], v[106:109]
	v_mfma_f32_16x16x32_bf16 v[114:117], v[176:179], v[220:223], v[114:117]
	v_mfma_f32_16x16x32_bf16 v[114:117], v[180:183], v[224:227], v[114:117]
	v_mfma_f32_16x16x32_bf16 v[102:105], v[168:171], v[220:223], v[102:105]
	v_mfma_f32_16x16x32_bf16 v[102:105], v[172:175], v[224:227], v[102:105]
	v_mfma_f32_16x16x32_bf16 v[110:113], v[144:147], v[220:223], v[110:113]
	v_mfma_f32_16x16x32_bf16 v[110:113], v[148:151], v[224:227], v[110:113]
	v_mfma_f32_16x16x32_bf16 v[94:97], v[144:147], v[228:231], v[94:97]
	v_mfma_f32_16x16x32_bf16 v[94:97], v[148:151], v[232:235], v[94:97]
	v_mfma_f32_16x16x32_bf16 v[86:89], v[168:171], v[228:231], v[86:89]
	v_mfma_f32_16x16x32_bf16 v[86:89], v[172:175], v[232:235], v[86:89]
	v_mfma_f32_16x16x32_bf16 v[98:101], v[176:179], v[228:231], v[98:101]
	v_mfma_f32_16x16x32_bf16 v[98:101], v[180:183], v[232:235], v[98:101]
	v_mfma_f32_16x16x32_bf16 v[90:93], v[184:187], v[228:231], v[90:93]
	v_mfma_f32_16x16x32_bf16 v[90:93], v[188:191], v[232:235], v[90:93]
	v_mfma_f32_16x16x32_bf16 v[74:77], v[184:187], v[236:239], v[74:77]
	v_mfma_f32_16x16x32_bf16 v[74:77], v[188:191], v[240:243], v[74:77]
	v_mfma_f32_16x16x32_bf16 v[82:85], v[176:179], v[236:239], v[82:85]
	v_mfma_f32_16x16x32_bf16 v[82:85], v[180:183], v[240:243], v[82:85]
	v_mfma_f32_16x16x32_bf16 v[70:73], v[168:171], v[236:239], v[70:73]
	v_mfma_f32_16x16x32_bf16 v[70:73], v[172:175], v[240:243], v[70:73]
	v_mfma_f32_16x16x32_bf16 v[78:81], v[144:147], v[236:239], v[78:81]
	v_mfma_f32_16x16x32_bf16 v[78:81], v[148:151], v[240:243], v[78:81]
	s_barrier
; #define PG8_STAGE(bufoff, gbase, voff) do { _Pragma("unroll") for (int _i = 0; _i < 2; ++_i) \
;         __builtin_amdgcn_global_load_lds((const unsigned*)((const char*)(gbase) + (voff)[_i]), (PG8_LAS unsigned*)(lds + (bufoff) + ldsw + _i * 8192), 16, 0, 0); } while (0)
; #define PG8_LDA(dst, b, h) do { _Pragma("unroll") for (int m = 0; m < 4; ++m) _Pragma("unroll") for (int k = 0; k < 2; ++k) dst[m][k] = *(const PG8_LAS bf16x8*)(lds + PG8_SA(b, h) + aoff + m * 2048 + k * 1024); } while (0)
; #define PG8_MMA(ai, bj, At, Bt) do { __builtin_amdgcn_s_setprio(1); _Pragma("unroll") for (int m = 0; m < 4; ++m) _Pragma("unroll") for (int n = 0; n < 2; ++n) _Pragma("unroll") for (int k = 0; k < 2; ++k) \
;         acc[ai][bj][m][n] = __builtin_amdgcn_mfma_f32_16x16x32_bf16(Bt[n][k], At[m][k], acc[ai][bj][m][n], 0, 0, 0); __builtin_amdgcn_s_setprio(0); } while (0)
; #define PG8_WAIT_V(n) asm volatile("s_waitcnt vmcnt(" #n ")" ::: "memory")
; #define PG8_WAIT_L(n) asm volatile("s_waitcnt lgkmcnt(" #n ")" ::: "memory")
; #define PG8_BAR __builtin_amdgcn_s_barrier()
; #define PG8_SCHED __builtin_amdgcn_sched_barrier(0)
; template <class Epi, class Sched, bool ALIGN_EPI = false, bool SP2 = false>
; __device__ __forceinline__ void gemm_phase(PG8_LAS unsigned char* lds, const Gemm g, const Sched& S, const Epi& E) {
;     ...
;         for (int t = 0; t < nt; t += 2) {
;     ...
;             PG8_LDA(At, 1, 1); PG8_STAGE(PG8_SB(1, 0), b3, voffB); PG8_STAGE(PG8_SB(1, 1), b3 + hstep, voffB); PG8_STAGE(PG8_SA(1, 0), a3, voffA);
;             PG8_WAIT_V(8); PG8_WAIT_L(0); PG8_BAR; PG8_MMA(1, 0, At, B0); PG8_MMA(1, 1, At, B1); PG8_BAR; PG8_SCHED;
	ds_read_b128 v[212:215], v157 offset:49152
	ds_read_b128 v[216:219], v157 offset:50176
	ds_read_b128 v[220:223], v157 offset:51200
	ds_read_b128 v[224:227], v157 offset:52224
	ds_read_b128 v[228:231], v157 offset:53248
	ds_read_b128 v[232:235], v157 offset:54272
	ds_read_b128 v[236:239], v157 offset:55296
	ds_read_b128 v[240:243], v157 offset:56320
	s_add_i32 s4, s4, s65
	s_add_i32 m0, s4, 0xffffff80
	s_nop 0
	global_load_lds_dwordx4 v4, s[22:23] offset:128
	s_add_i32 m0, s4, 0x1f80
	s_add_i32 s4, s5, s65
	global_load_lds_dwordx4 v2, s[22:23] offset:128
	s_add_u32 s22, s22, 0x80080
	s_addc_u32 s23, s23, 0
	s_mov_b32 m0, s4
	s_nop 0
	global_load_lds_dwordx4 v4, s[22:23]
	s_add_i32 m0, s4, 0x2000
	s_nop 0
	global_load_lds_dwordx4 v2, s[22:23]
	s_add_i32 m0, s3, 0xffffff80
	s_nop 0
	global_load_lds_dwordx4 v136, s[56:57] offset:128
	s_add_i32 m0, s75, 0xffffff80
	s_nop 0
	global_load_lds_dwordx4 v134, s[56:57] offset:128
	s_waitcnt vmcnt(8)
	s_waitcnt lgkmcnt(0)
	s_barrier
	v_mfma_f32_16x16x32_bf16 v[62:65], v[144:147], v[212:215], v[62:65]
	v_mfma_f32_16x16x32_bf16 v[62:65], v[148:151], v[216:219], v[62:65]
	v_mfma_f32_16x16x32_bf16 v[54:57], v[168:171], v[212:215], v[54:57]
	v_mfma_f32_16x16x32_bf16 v[54:57], v[172:175], v[216:219], v[54:57]
	v_mfma_f32_16x16x32_bf16 v[66:69], v[176:179], v[212:215], v[66:69]
	v_mfma_f32_16x16x32_bf16 v[66:69], v[180:183], v[216:219], v[66:69]
	v_mfma_f32_16x16x32_bf16 v[58:61], v[184:187], v[212:215], v[58:61]
	v_mfma_f32_16x16x32_bf16 v[58:61], v[188:191], v[216:219], v[58:61]
	v_mfma_f32_16x16x32_bf16 v[42:45], v[184:187], v[220:223], v[42:45]
	v_mfma_f32_16x16x32_bf16 v[42:45], v[188:191], v[224:227], v[42:45]
	v_mfma_f32_16x16x32_bf16 v[50:53], v[176:179], v[220:223], v[50:53]
	v_mfma_f32_16x16x32_bf16 v[50:53], v[180:183], v[224:227], v[50:53]
	v_mfma_f32_16x16x32_bf16 v[38:41], v[168:171], v[220:223], v[38:41]
	v_mfma_f32_16x16x32_bf16 v[38:41], v[172:175], v[224:227], v[38:41]
	v_mfma_f32_16x16x32_bf16 v[46:49], v[144:147], v[220:223], v[46:49]
	v_mfma_f32_16x16x32_bf16 v[46:49], v[148:151], v[224:227], v[46:49]
	v_mfma_f32_16x16x32_bf16 v[30:33], v[144:147], v[228:231], v[30:33]
	v_mfma_f32_16x16x32_bf16 v[30:33], v[148:151], v[232:235], v[30:33]
	v_mfma_f32_16x16x32_bf16 v[22:25], v[168:171], v[228:231], v[22:25]
	v_mfma_f32_16x16x32_bf16 v[22:25], v[172:175], v[232:235], v[22:25]
	v_mfma_f32_16x16x32_bf16 v[34:37], v[176:179], v[228:231], v[34:37]
	v_mfma_f32_16x16x32_bf16 v[34:37], v[180:183], v[232:235], v[34:37]
	v_mfma_f32_16x16x32_bf16 v[26:29], v[184:187], v[228:231], v[26:29]
	v_mfma_f32_16x16x32_bf16 v[26:29], v[188:191], v[232:235], v[26:29]
	v_mfma_f32_16x16x32_bf16 v[10:13], v[184:187], v[236:239], v[10:13]
	v_mfma_f32_16x16x32_bf16 v[10:13], v[188:191], v[240:243], v[10:13]
	v_mfma_f32_16x16x32_bf16 v[18:21], v[176:179], v[236:239], v[18:21]
	v_mfma_f32_16x16x32_bf16 v[18:21], v[180:183], v[240:243], v[18:21]
	v_mfma_f32_16x16x32_bf16 v[6:9], v[168:171], v[236:239], v[6:9]
	v_mfma_f32_16x16x32_bf16 v[6:9], v[172:175], v[240:243], v[6:9]
	v_mfma_f32_16x16x32_bf16 v[14:17], v[144:147], v[236:239], v[14:17]
	v_mfma_f32_16x16x32_bf16 v[14:17], v[148:151], v[240:243], v[14:17]
	s_barrier
	s_add_i32 s20, s20, 2
	s_add_u32 s54, s54, 0x100
	s_addc_u32 s55, s55, 0
	s_add_u32 s71, s71, 0x100
	s_addc_u32 s77, s77, 0
	s_cmp_gt_u32 s20, 29
	s_cbranch_scc0 .LBB0_216
	s_and_b64 vcc, exec, s[44:45]
	s_movk_i32 s77, 0x6000
	s_mov_b32 s71, 0x44800000
	s_cbranch_vccz .LBB0_219
	s_barrier
